# P2x RWKV sample iteration: previous-row group also deferred behind the iteration's single wait (flag-guarded conversion), one memory round trip less per iteration
# baseline (speedup 1.0000x reference)
.LBB0_617:
	s_mov_b64 s[98:99], 0
	v_mov_b32_e32 v191, 0
	v_mov_b32_e32 v192, 0
	v_mov_b32_e32 v193, 0
	v_mov_b32_e32 v194, 0
	v_mov_b32_e32 v195, 0
	v_mov_b32_e32 v196, 0
	v_mov_b32_e32 v197, 0
	v_mov_b32_e32 v198, 0
	v_mov_b32_e32 v199, 0
	v_mov_b32_e32 v200, 0
	v_mov_b32_e32 v201, 0
	v_mov_b32_e32 v202, 0
	v_mov_b32_e32 v203, 0
	v_mov_b32_e32 v204, 0
	v_mov_b32_e32 v205, 0
	v_mov_b32_e32 v206, 0
	v_mov_b32_e32 v207, 0
	v_mov_b32_e32 v211, 0
	v_mov_b32_e32 v212, 0
	v_mov_b32_e32 v213, 0
	s_ashr_i32 s0, s43, 3
	s_ashr_i32 s1, s0, 31
	s_lshl_b64 s[2:3], s[0:1], 9
	s_and_b32 s82, s74, 0x1c0
	v_or_b32_e32 v0, s2, v54
	v_or_b32_e32 v16, s82, v158
	v_readlane_b32 s44, v250, 23
	v_mov_b32_e32 v23, s3
	v_or_b32_e32 v22, s82, v0
	v_lshlrev_b32_e32 v20, 2, v16
	v_readlane_b32 s45, v250, 24
	v_lshlrev_b64 v[0:1], 8, v[22:23]
	v_lshl_add_u64 v[0:1], v[58:59], 0, v[0:1]
	v_lshl_add_u64 v[16:17], s[44:45], 0, v[20:21]
	v_add_co_u32_e32 v16, vcc, 0x1000, v16
	global_load_dwordx4 v[12:15], v[0:1], off
	global_load_dwordx4 v[8:11], v[0:1], off offset:64
	global_load_dwordx4 v[4:7], v[0:1], off offset:128
	s_nop 0
	global_load_dwordx4 v[0:3], v[0:1], off offset:192
	v_readlane_b32 s56, v250, 35
	v_readlane_b32 s57, v250, 36
	v_readlane_b32 s58, v250, 37
	v_readlane_b32 s59, v250, 38
	v_addc_co_u32_e32 v17, vcc, 0, v17, vcc
	global_load_dword v47, v20, s[44:45]
	global_load_dword v45, v20, s[44:45] offset:2048
	global_load_dword v43, v20, s[56:57]
	s_nop 0
	global_load_dword v42, v20, s[58:59]
	global_load_dword v46, v[16:17], off
	v_readlane_b32 s44, v249, 60
	v_readlane_b32 s45, v249, 61
	s_and_b32 s1, s43, -8
	s_mov_b64 s[2:3], -1
	s_and_b64 vcc, exec, s[44:45]
	v_readlane_b32 s46, v250, 25
	v_readlane_b32 s47, v250, 26
	v_readlane_b32 s48, v250, 27
	v_readlane_b32 s49, v250, 28
	v_readlane_b32 s50, v250, 29
	v_readlane_b32 s51, v250, 30
	v_readlane_b32 s52, v250, 31
	v_readlane_b32 s53, v250, 32
	v_readlane_b32 s54, v250, 33
	v_readlane_b32 s55, v250, 34
	s_cbranch_vccz .LBB0_620
	s_andn2_b64 vcc, exec, s[72:73]
	s_cbranch_vccnz .LBB0_647
	s_add_i32 s2, s1, 0x4003
	s_mul_hi_i32 s3, s2, 0xe00
	s_mulk_i32 s2, 0xe00
	s_add_u32 s2, s60, s2
	s_addc_u32 s3, s61, s3
	s_lshl_b32 s44, s82, 1
	s_add_u32 s2, s2, s44
	s_addc_u32 s3, s3, 0
	global_load_ushort v214, v48, s[2:3]
	global_load_ushort v215, v48, s[2:3] offset:1024
	global_load_ushort v216, v48, s[2:3] offset:2048
	s_mov_b64 s[2:3], 0
	s_mov_b64 s[98:99], -1

.LBB0_631:
	s_waitcnt vmcnt(0)
	v_lshlrev_b32_e32 v29, 16, v191
	v_lshlrev_b32_e32 v30, 16, v192
	v_lshlrev_b32_e32 v31, 16, v193
	v_lshlrev_b32_e32 v37, 16, v194
	v_lshlrev_b32_e32 v36, 16, v195
	v_lshlrev_b32_e32 v18, 16, v196
	v_lshlrev_b32_e32 v26, 16, v197
	v_lshlrev_b32_e32 v27, 16, v198
	v_lshlrev_b32_e32 v51, 16, v199
	v_lshlrev_b32_e32 v34, 16, v200
	v_lshlrev_b32_e32 v49, 16, v201
	v_lshlrev_b32_e32 v24, 16, v202
	v_lshlrev_b32_e32 v25, 16, v203
	v_lshlrev_b32_e32 v66, 16, v204
	v_lshlrev_b32_e32 v28, 16, v205
	v_lshlrev_b32_e32 v19, 16, v206
	v_lshlrev_b32_e32 v20, 16, v207
	v_lshlrev_b32_e32 v17, 16, v211
	v_lshlrev_b32_e32 v70, 16, v212
	v_lshlrev_b32_e32 v16, 16, v213
	s_and_b64 vcc, exec, s[98:99]
	s_cbranch_vccz .Lsamp0_skip
	v_lshlrev_b32_e32 v35, 16, v214
	v_lshlrev_b32_e32 v33, 16, v215
	v_lshlrev_b32_e32 v32, 16, v216
